# attention unit epilogue: the eight subln gain loads issued together (were four serialized load/wait/store round trips per unit)
# baseline (speedup 1.0000x reference)
; #define LAS __attribute__((address_space(3)))
; __device__ __forceinline__ u32x4 pack8(const f32x4 a, const f32x4 b) { u32x4 w; w.x = cvtpk(a[0], a[1]); w.y = cvtpk(a[2], a[3]); w.z = cvtpk(b[0], b[1]); w.w = cvtpk(b[2], b[3]); return w; }
; __device__ __forceinline__ void attn_phase(LAS unsigned char* lds, const AttnArgs& a, int tid_in) {
;     ...
;         {
;             const int row = 16 * wid + (lane >> 2), qd = lane & 3, tq = 128 * qb + row;
;             f32x4 v[8]; float ss = 0.f;
; #pragma unroll
;             for (int j = 0; j < 8; ++j) { v[j] = *(const LAS f32x4*)(S + row * SSTR + 32 * qd + 4 * j); ss += (v[j][0] * v[j][0] + v[j][1] * v[j][1]) + (v[j][2] * v[j][2] + v[j][3] * v[j][3]); }
;             ss += __shfl_xor(ss, 1); ss += __shfl_xor(ss, 2);
;             const float rn = rsqrtf(ss * (1.0f / 128.0f) + EPS) * a.osc;
;             if (tq < TT) {
;                 bf16_t* op = a.MIX + (rowb + tq) * DM + h * 128 + 32 * qd;
; #pragma unroll
;                 for (int j = 0; j < 4; ++j) { const f32x4 g0 = *(const f32x4*)(a.subg + 32 * qd + 8 * j), g1 = *(const f32x4*)(a.subg + 32 * qd + 8 * j + 4);
;                     *(u32x4*)(op + 8 * j) = pack8(v[2 * j] * rn * g0, v[2 * j + 1] * rn * g1); }
;             }
.LBB0_608:
	s_waitcnt lgkmcnt(0)
	s_barrier
	ds_read_b128 v[36:39], v235
	ds_read_b128 v[32:35], v235 offset:16
	ds_read_b128 v[6:9], v235 offset:32
	ds_read_b128 v[2:5], v235 offset:48
	ds_read_b128 v[44:47], v235 offset:96
	ds_read_b128 v[48:51], v235 offset:112
	s_waitcnt lgkmcnt(5)
	v_mul_f32_e32 v0, v37, v37
	v_mul_f32_e32 v10, v39, v39
	v_fmac_f32_e32 v0, v36, v36
	v_fmac_f32_e32 v10, v38, v38
	v_add_f32_e32 v0, v0, v10
	s_waitcnt lgkmcnt(4)
	v_mul_f32_e32 v10, v33, v33
	v_mul_f32_e32 v11, v35, v35
	v_fmac_f32_e32 v10, v32, v32
	v_fmac_f32_e32 v11, v34, v34
	v_add_f32_e32 v10, v10, v11
	v_add_f32_e32 v0, v0, v10
	s_waitcnt lgkmcnt(3)
	v_mul_f32_e32 v10, v7, v7
	v_mul_f32_e32 v11, v9, v9
	v_fmac_f32_e32 v10, v6, v6
	v_fmac_f32_e32 v11, v8, v8
	v_add_f32_e32 v10, v10, v11
	v_add_f32_e32 v0, v0, v10
	s_waitcnt lgkmcnt(2)
	v_mul_f32_e32 v10, v3, v3
	v_mul_f32_e32 v11, v5, v5
	v_fmac_f32_e32 v10, v2, v2
	v_fmac_f32_e32 v11, v4, v4
	v_add_f32_e32 v10, v10, v11
	v_add_f32_e32 v0, v0, v10
	ds_read_b128 v[10:13], v235 offset:64
	ds_read_b128 v[40:43], v235 offset:80
	v_cmp_lt_i32_e32 vcc, v216, v217
	s_waitcnt lgkmcnt(1)
	v_mul_f32_e32 v14, v11, v11
	v_mul_f32_e32 v15, v13, v13
	v_fmac_f32_e32 v14, v10, v10
	v_fmac_f32_e32 v15, v12, v12
	v_add_f32_e32 v14, v14, v15
	v_add_f32_e32 v0, v0, v14
	s_waitcnt lgkmcnt(0)
	v_mul_f32_e32 v14, v41, v41
	v_mul_f32_e32 v15, v43, v43
	v_fmac_f32_e32 v14, v40, v40
	v_fmac_f32_e32 v15, v42, v42
	v_add_f32_e32 v14, v14, v15
	v_add_f32_e32 v0, v0, v14
	v_mul_f32_e32 v14, v45, v45
	v_mul_f32_e32 v15, v47, v47
	v_fmac_f32_e32 v14, v44, v44
	v_fmac_f32_e32 v15, v46, v46
	v_add_f32_e32 v14, v14, v15
	v_add_f32_e32 v0, v0, v14
	v_mul_f32_e32 v14, v49, v49
	v_mul_f32_e32 v15, v51, v51
	v_fmac_f32_e32 v14, v48, v48
	v_fmac_f32_e32 v15, v50, v50
	v_add_f32_e32 v14, v14, v15
	v_cndmask_b32_e32 v15, v215, v216, vcc
	v_add_f32_e32 v0, v0, v14
	v_lshlrev_b32_e32 v15, 2, v15
	ds_bpermute_b32 v15, v15, v0
	v_lshl_add_u32 v14, s3, 7, v227
	s_movk_i32 s3, 0x2010
	s_waitcnt lgkmcnt(0)
	v_add_f32_e32 v0, v0, v15
	v_xor_b32_e32 v15, 2, v215
	v_cmp_lt_i32_e32 vcc, v15, v217
	s_nop 1
	v_cndmask_b32_e32 v15, v215, v15, vcc
	v_lshlrev_b32_e32 v15, 2, v15
	ds_bpermute_b32 v15, v15, v0
	v_cmp_gt_i32_e32 vcc, s3, v14
	s_and_saveexec_b64 s[42:43], vcc
	s_cbranch_execz .LBB0_572
	global_load_dwordx4 v[52:55], v[206:207], off
	global_load_dwordx4 v[56:59], v[206:207], off offset:16
	global_load_dwordx4 v[64:67], v[206:207], off offset:32
	global_load_dwordx4 v[68:71], v[206:207], off offset:48
	global_load_dwordx4 v[72:75], v[206:207], off offset:64
	global_load_dwordx4 v[76:79], v[206:207], off offset:80
	global_load_dwordx4 v[80:83], v[206:207], off offset:96
	global_load_dwordx4 v[84:87], v[206:207], off offset:112
	s_waitcnt lgkmcnt(0)
	v_add_f32_e32 v0, v0, v15
	v_fmamk_f32 v0, v0, 0x3c000000, v214
	s_mov_b32 s3, 0x800000
	v_mul_f32_e32 v60, 0x4b800000, v0
	v_cmp_gt_f32_e32 vcc, s3, v0
	v_ashrrev_i32_e32 v15, 31, v14
	v_lshl_add_u64 v[14:15], s[10:11], 0, v[14:15]
	v_cndmask_b32_e32 v0, v0, v60, vcc
	v_rsq_f32_e32 v0, v0
	v_readlane_b32 s10, v252, 51
	s_lshl_b32 s30, s33, 7
	v_lshlrev_b64 v[14:15], 11, v[14:15]
	v_mul_f32_e32 v60, 0x45800000, v0
	v_cndmask_b32_e32 v0, v0, v60, vcc
	v_readlane_b32 s11, v252, 52
	v_mul_f32_e32 v0, v222, v0
	s_ashr_i32 s31, s30, 31
	v_lshl_add_u64 v[14:15], s[10:11], 0, v[14:15]
	v_pk_mul_f32 v[36:37], v[36:37], v[0:1] op_sel_hi:[1,0]
	v_pk_mul_f32 v[38:39], v[38:39], v[0:1] op_sel_hi:[1,0]
	v_pk_mul_f32 v[32:33], v[32:33], v[0:1] op_sel_hi:[1,0]
	v_pk_mul_f32 v[34:35], v[34:35], v[0:1] op_sel_hi:[1,0]
	v_mov_b32_e32 v209, v1
	v_lshl_add_u64 v[14:15], s[30:31], 1, v[14:15]
	v_lshl_add_u64 v[14:15], v[14:15], 0, v[208:209]
	v_pk_mul_f32 v[6:7], v[6:7], v[0:1] op_sel_hi:[1,0]
	v_pk_mul_f32 v[8:9], v[8:9], v[0:1] op_sel_hi:[1,0]
	v_pk_mul_f32 v[2:3], v[2:3], v[0:1] op_sel_hi:[1,0]
	v_pk_mul_f32 v[4:5], v[4:5], v[0:1] op_sel_hi:[1,0]
	v_pk_mul_f32 v[10:11], v[10:11], v[0:1] op_sel_hi:[1,0]
	v_pk_mul_f32 v[12:13], v[12:13], v[0:1] op_sel_hi:[1,0]
	s_waitcnt vmcnt(7)
	v_pk_mul_f32 v[38:39], v[38:39], v[54:55]
	v_pk_mul_f32 v[36:37], v[36:37], v[52:53]
	s_waitcnt vmcnt(6)
	v_pk_mul_f32 v[52:53], v[34:35], v[58:59]
	v_pk_mul_f32 v[34:35], v[32:33], v[56:57]
	v_cvt_pk_bf16_f32 v32, v36, v37
	v_cvt_pk_bf16_f32 v33, v38, v39
	v_cvt_pk_bf16_f32 v34, v34, v35
	v_cvt_pk_bf16_f32 v35, v52, v53
	global_store_dwordx4 v[14:15], v[32:35], off
	s_waitcnt vmcnt(6)
	v_pk_mul_f32 v[8:9], v[8:9], v[66:67]
	v_pk_mul_f32 v[6:7], v[6:7], v[64:65]
	s_waitcnt vmcnt(5)
	v_pk_mul_f32 v[32:33], v[4:5], v[70:71]
	v_pk_mul_f32 v[4:5], v[2:3], v[68:69]
	v_cvt_pk_bf16_f32 v2, v6, v7
	v_cvt_pk_bf16_f32 v3, v8, v9
	v_cvt_pk_bf16_f32 v4, v4, v5
	v_cvt_pk_bf16_f32 v5, v32, v33
	global_store_dwordx4 v[14:15], v[2:5], off offset:16
	v_pk_mul_f32 v[32:33], v[40:41], v[0:1] op_sel_hi:[1,0]
	v_pk_mul_f32 v[34:35], v[42:43], v[0:1] op_sel_hi:[1,0]
	s_waitcnt vmcnt(5)
	v_pk_mul_f32 v[4:5], v[12:13], v[74:75]
	v_pk_mul_f32 v[2:3], v[10:11], v[72:73]
	s_waitcnt vmcnt(4)
	v_pk_mul_f32 v[8:9], v[34:35], v[78:79]
	v_pk_mul_f32 v[6:7], v[32:33], v[76:77]
	v_cvt_pk_bf16_f32 v2, v2, v3
	v_cvt_pk_bf16_f32 v3, v4, v5
	v_cvt_pk_bf16_f32 v4, v6, v7
	v_cvt_pk_bf16_f32 v5, v8, v9
	global_store_dwordx4 v[14:15], v[2:5], off offset:32
	v_pk_mul_f32 v[10:11], v[44:45], v[0:1] op_sel_hi:[1,0]
	v_pk_mul_f32 v[12:13], v[46:47], v[0:1] op_sel_hi:[1,0]
	v_pk_mul_f32 v[32:33], v[48:49], v[0:1] op_sel_hi:[1,0]
	v_pk_mul_f32 v[34:35], v[50:51], v[0:1] op_sel_hi:[1,0]
	s_waitcnt vmcnt(4)
	v_pk_mul_f32 v[4:5], v[12:13], v[82:83]
	v_pk_mul_f32 v[2:3], v[10:11], v[80:81]
	s_waitcnt vmcnt(3)
	v_pk_mul_f32 v[8:9], v[34:35], v[86:87]
	v_pk_mul_f32 v[6:7], v[32:33], v[84:85]
	v_cvt_pk_bf16_f32 v2, v2, v3
	v_cvt_pk_bf16_f32 v3, v4, v5
	v_cvt_pk_bf16_f32 v4, v6, v7
	v_cvt_pk_bf16_f32 v5, v8, v9
	global_store_dwordx4 v[14:15], v[2:5], off offset:48
	s_branch .LBB0_572
